# prep: odd workgroups run the w_in transpose before the x conversion (even keep the order) so latency-bound and bandwidth-bound work overlap across the grid
# speedup vs baseline: 1.0005x; 1.0005x over previous
.LBB0_5:
	s_or_b64 exec, exec, s[0:1]
	s_bitcmp1_b32 s86, 0
	s_cbranch_scc1 .Lmy_pw_first
.Lmy_px_second:
	v_lshrrev_b32_e32 v1, 6, v0
	v_and_b32_e32 v158, 63, v0
	v_lshl_or_b32 v2, s86, 3, v1
	s_mov_b32 s0, 0x8000
	s_lshl_b32 s4, s82, 3
	v_cmp_gt_i32_e32 vcc, s0, v2
	v_lshlrev_b32_e32 v146, 3, v158
	v_lshlrev_b32_e32 v148, 4, v158
	s_and_saveexec_b64 s[6:7], vcc
	s_cbranch_execz .LBB0_8
	v_mbcnt_lo_u32_b32 v1, -1, 0
	v_mbcnt_hi_u32_b32 v4, -1, v1
	v_and_b32_e32 v1, 64, v4
	v_add_u32_e32 v5, 64, v1
	v_xor_b32_e32 v1, 1, v4
	v_cmp_lt_i32_e32 vcc, v1, v5
	v_xor_b32_e32 v3, 2, v4
	v_xor_b32_e32 v6, 4, v4
	v_cndmask_b32_e32 v1, v4, v1, vcc
	v_cmp_lt_i32_e32 vcc, v3, v5
	v_mov_b32_e32 v147, 0
	v_mov_b32_e32 v149, v147
	v_cndmask_b32_e32 v3, v4, v3, vcc
	v_cmp_lt_i32_e32 vcc, v6, v5
	v_lshlrev_b32_e32 v1, 2, v1
	v_lshlrev_b32_e32 v3, 2, v3
	v_cndmask_b32_e32 v6, v4, v6, vcc
	v_lshlrev_b32_e32 v9, 2, v6
	v_xor_b32_e32 v6, 8, v4
	v_cmp_lt_i32_e32 vcc, v6, v5
	s_mov_b64 s[16:17], 0
	s_mov_b32 s18, 0x3a800000
	v_cndmask_b32_e32 v6, v4, v6, vcc
	v_lshlrev_b32_e32 v12, 2, v6
	v_xor_b32_e32 v6, 16, v4
	v_cmp_lt_i32_e32 vcc, v6, v5
	v_mov_b32_e32 v8, 0x358637bd
	s_mov_b32 s2, 0x800000
	v_cndmask_b32_e32 v6, v4, v6, vcc
	v_lshlrev_b32_e32 v13, 2, v6
	v_xor_b32_e32 v6, 32, v4
	v_cmp_lt_i32_e32 vcc, v6, v5
	s_movk_i32 s3, 0x7fff
	v_mov_b32_e32 v10, v2
	v_cndmask_b32_e32 v4, v4, v6, vcc
	v_lshlrev_b32_e32 v14, 2, v4
	v_lshl_add_u64 v[4:5], s[80:81], 0, v[146:147]
	v_lshl_add_u64 v[6:7], s[52:53], 0, v[148:149]

.LBB0_8:
	s_or_b64 exec, exec, s[6:7]
	s_bitcmp1_b32 s86, 0
	s_cbranch_scc1 .Lmy_px_done_odd
.Lmy_pw_first:
	s_lshl_b32 s0, s82, 9
	v_lshl_or_b32 v10, s86, 9, v0
	s_add_u32 s16, s80, 0x36000000
	s_mov_b32 s1, 0x90000
	s_addc_u32 s17, s81, 0
	v_cmp_gt_i32_e32 vcc, s1, v10
	s_and_saveexec_b64 s[6:7], vcc
	s_cbranch_execz .LBB0_30
	s_cmp_lg_u64 s[56:57], 0
	s_cbranch_scc1 .Lmy_w1_fast
	s_cselect_b64 s[2:3], -1, 0
	v_cndmask_b32_e64 v1, 0, 1, s[2:3]
	s_mov_b64 s[18:19], 0
	s_mov_b32 s1, 0x38e38e39
	v_cmp_ne_u32_e64 s[4:5], 1, v1
	s_mov_b32 s2, 0x8ffff
	v_mov_b32_e32 v9, v10
	s_branch .LBB0_14

.Lmy_px_done_odd:
	s_lshl_b32 s0, s82, 9
	v_lshl_or_b32 v10, s86, 9, v0
	s_add_u32 s16, s80, 0x36000000
	s_addc_u32 s17, s81, 0
	s_branch .Lmy_pw_after

.Lmy_pw_after:
	s_add_u32 s88, s80, 0x36900000
	s_addc_u32 s89, s81, 0
	s_add_u32 s84, s80, 0x36d00000
	s_addc_u32 s85, s81, 0
	s_add_u32 s12, s80, 0x36ec0000
	s_movk_i32 s1, 0x400
	s_addc_u32 s13, s81, 0
	v_cmp_gt_i32_e32 vcc, s1, v10
	s_and_saveexec_b64 s[4:5], vcc
	s_cbranch_execz .LBB0_57
	v_ashrrev_i32_e32 v11, 31, v10
	s_ashr_i32 s1, s0, 31
	v_lshlrev_b64 v[2:3], 2, v[10:11]
	s_lshl_b64 s[6:7], s[0:1], 2
	s_mov_b64 s[8:9], 0
	s_movk_i32 s1, 0x3ff
